# combined: K-loop saddr LDS-DMA + pipelined epilogues P7 P8 P9 P13 + exact SSD wait counts
# speedup vs baseline: 1.0050x; 1.0012x over previous
; #define LAS __attribute__((address_space(3)))
; __device__ __forceinline__ unsigned pkbf(float lo, float hi) { unsigned r; asm volatile("v_cvt_pk_bf16_f32 %0, %1, %2" : "=v"(r) : "v"(lo), "v"(hi)); return r; }
; __device__ __forceinline__ void ssd_unit(LAS char* L, int unit, const bf16* xbc, const float* dtb, const float* a_log, const float* dskip, bf16* yout, int tid_in) {
;     ...
;           for (int r = 0; r < 16; ++r) acc_h[r] = acc_h[r] * e_tot + (ha[r] + hb[r]); }
;         tidl = tid; asm volatile("" : "+v"(tidl));
;         if (more) {
;             const int a0 = off_b(32 * pb2 + l31, 4 * nb) + 8 * h;
; #pragma unroll
;             for (int q = 0; q < 4; ++q) { v2u o; o.x = pkbf(acc_h[4 * q], acc_h[4 * q + 1]); o.y = pkbf(acc_h[4 * q + 2], acc_h[4 * q + 3]);
;                 *(LAS v2u*)(L + H_OFF + (a0 ^ (16 * q))) = o; }
;             SSD_STAGE((ci + 1) & 1);
;             if (ci + 2 < SEQ / 128) SSD_PREFETCH(ci + 2);
;         }
;         __syncthreads();
.LBB0_714:
	v_pk_add_f32 v[12:13], v[12:13], v[28:29]
	v_pk_add_f32 v[10:11], v[10:11], v[26:27]
	v_pk_add_f32 v[8:9], v[8:9], v[24:25]
	v_pk_add_f32 v[6:7], v[6:7], v[22:23]
	v_pk_add_f32 v[4:5], v[4:5], v[20:21]
	v_pk_add_f32 v[2:3], v[2:3], v[18:19]
	v_pk_add_f32 v[0:1], v[0:1], v[16:17]
	v_pk_fma_f32 v[138:139], v[138:139], v[150:151], v[2:3] op_sel_hi:[1,0,1]
	v_pk_fma_f32 v[136:137], v[136:137], v[150:151], v[0:1] op_sel_hi:[1,0,1]
	v_pk_fma_f32 v[140:141], v[140:141], v[150:151], v[4:5] op_sel_hi:[1,0,1]
	v_pk_fma_f32 v[142:143], v[142:143], v[150:151], v[6:7] op_sel_hi:[1,0,1]
	v_pk_fma_f32 v[144:145], v[144:145], v[150:151], v[8:9] op_sel_hi:[1,0,1]
	v_pk_fma_f32 v[146:147], v[146:147], v[150:151], v[10:11] op_sel_hi:[1,0,1]
	s_andn2_b64 vcc, exec, s[2:3]
	v_pk_fma_f32 v[148:149], v[148:149], v[150:151], v[12:13] op_sel_hi:[1,0,1]
	s_cbranch_vccnz .LBB0_683
	v_cvt_pk_bf16_f32 v0, v136, v137
	v_cvt_pk_bf16_f32 v1, v138, v139
	ds_write_b64 v207, v[0:1]
	v_cvt_pk_bf16_f32 v0, v140, v141
	v_cvt_pk_bf16_f32 v1, v142, v143
	ds_write_b64 v208, v[0:1]
	v_cvt_pk_bf16_f32 v0, v144, v145
	v_cvt_pk_bf16_f32 v1, v146, v147
	ds_write_b64 v209, v[0:1]
	v_cvt_pk_bf16_f32 v0, v148, v149
	v_cvt_pk_bf16_f32 v1, v134, v135
	ds_write_b64 v210, v[0:1]
	v_ashrrev_i32_e32 v1, 4, v14
	v_lshlrev_b32_e32 v3, 2, v1
	v_and_b32_e32 v0, 15, v14
	v_and_b32_e32 v3, 12, v3
	v_bfe_u32 v4, v1, 2, 2
	v_lshlrev_b32_e32 v2, 8, v1
	v_bitop3_b32 v3, v3, v0, v4 bitop3:0x36
	v_lshl_or_b32 v2, v3, 4, v2
	v_ashrrev_i32_e32 v3, 3, v14
	s_add_i32 s33, s75, 0x800
	v_add_u32_e32 v2, 0, v2
	v_lshlrev_b32_e32 v5, 2, v3
	s_and_b32 s2, s33, 0x800
	s_waitcnt vmcnt(11)
	ds_write_b128 v2, v[56:59]
	s_waitcnt vmcnt(10)
	ds_write_b128 v2, v[60:63] offset:32768
	s_waitcnt vmcnt(9)
	ds_write_b128 v2, v[64:67] offset:8192
	s_waitcnt vmcnt(8)
	ds_write_b128 v2, v[68:71] offset:40960
	s_waitcnt vmcnt(7)
	ds_write_b128 v2, v[72:75] offset:16384
	s_waitcnt vmcnt(6)
	ds_write_b128 v2, v[76:79] offset:49152
	s_waitcnt vmcnt(5)
	ds_write_b128 v2, v[80:83] offset:24576
	s_waitcnt vmcnt(4)
	ds_write_b128 v2, v[84:87] offset:57344
	v_and_b32_e32 v2, 7, v14
	v_and_b32_e32 v6, 12, v5
	v_bfe_u32 v7, v3, 2, 2
	s_add_i32 s2, s2, 0
	v_bitop3_b32 v6, v6, v2, v7 bitop3:0x36
	s_add_i32 s2, s2, 0x1c000
	v_lshlrev_b32_e32 v4, 8, v3
	v_lshlrev_b32_e32 v6, 4, v6
	v_or_b32_e32 v7, v6, v4
	v_add_u32_e32 v8, s2, v5
	v_add_u32_e32 v9, s52, v7
	ds_read_b32 v7, v8 offset:1024
	v_bitop3_b32 v4, v6, s63, v4 bitop3:0x36
	v_add_u32_e32 v10, s52, v4
	v_lshlrev_b32_e32 v4, 16, v48
	v_and_b32_e32 v5, 0xffff0000, v48
	s_waitcnt lgkmcnt(0)
	v_mul_f32_e32 v4, v7, v4
	v_mul_f32_e32 v5, v7, v5
	ds_write_b128 v9, v[48:51]
	v_cvt_pk_bf16_f32 v4, v4, v5
	v_lshlrev_b32_e32 v5, 16, v49
	v_and_b32_e32 v6, 0xffff0000, v49
	v_mul_f32_e32 v5, v7, v5
	v_mul_f32_e32 v6, v7, v6
	v_cvt_pk_bf16_f32 v5, v5, v6
	v_lshlrev_b32_e32 v6, 16, v50
	v_and_b32_e32 v11, 0xffff0000, v50
	v_mul_f32_e32 v6, v7, v6
	v_mul_f32_e32 v11, v7, v11
	v_cvt_pk_bf16_f32 v6, v6, v11
	v_lshlrev_b32_e32 v11, 16, v51
	v_and_b32_e32 v12, 0xffff0000, v51
	v_mul_f32_e32 v11, v7, v11
	v_mul_f32_e32 v7, v7, v12
	v_cvt_pk_bf16_f32 v7, v11, v7
	ds_write_b128 v10, v[4:7]
	ds_read_b32 v7, v8 offset:1280
	v_lshlrev_b32_e32 v4, 16, v52
	v_and_b32_e32 v5, 0xffff0000, v52
	ds_write_b128 v9, v[52:55] offset:16384
	v_and_b32_e32 v6, 0xffff0000, v53
	s_waitcnt lgkmcnt(1)
	v_mul_f32_e32 v4, v7, v4
	v_mul_f32_e32 v5, v7, v5
	v_cvt_pk_bf16_f32 v4, v4, v5
	v_lshlrev_b32_e32 v5, 16, v53
	v_mul_f32_e32 v5, v7, v5
	v_mul_f32_e32 v6, v7, v6
	v_cvt_pk_bf16_f32 v5, v5, v6
	v_lshlrev_b32_e32 v6, 16, v54
	v_and_b32_e32 v8, 0xffff0000, v54
	v_mul_f32_e32 v6, v7, v6
	v_mul_f32_e32 v8, v7, v8
	v_cvt_pk_bf16_f32 v6, v6, v8
	v_lshlrev_b32_e32 v8, 16, v55
	v_and_b32_e32 v9, 0xffff0000, v55
	v_mul_f32_e32 v8, v7, v8
	v_mul_f32_e32 v7, v7, v9
	s_andn2_b64 vcc, exec, s[66:67]
	v_cvt_pk_bf16_f32 v7, v8, v7
	ds_write_b128 v10, v[4:7] offset:16384
	s_cbranch_vccnz .LBB0_683
	s_add_i32 s50, s87, 0x100
	s_and_b64 s[2:3], s[76:77], exec
	s_cselect_b32 s2, s50, s86
	s_add_i32 s50, s2, s71
	v_mul_lo_u32 v3, v3, s68
	v_add_u32_e32 v3, s50, v3
	v_lshl_or_b32 v2, v2, 4, s80
	v_mad_u64_u32 v[2:3], s[2:3], v3, s69, v[2:3]
	v_mul_lo_u32 v1, v1, s68
	s_mul_i32 s2, s68, 0x140000
	v_add_u32_e32 v1, s50, v1
	v_lshl_or_b32 v0, v0, 4, s82
	v_add_u32_e32 v3, s2, v2
	v_mad_u64_u32 v[0:1], s[2:3], v1, s69, v[0:1]
	global_load_dwordx4 v[48:51], v2, s[96:97]
	global_load_dwordx4 v[52:55], v3, s[96:97]
	global_load_dwordx4 v[56:59], v0, s[96:97]
	global_load_dwordx4 v[60:63], v0, s[96:97] offset:2048
	v_add_u32_e32 v0, s83, v0
	global_load_dwordx4 v[64:67], v0, s[96:97]
	global_load_dwordx4 v[68:71], v0, s[96:97] offset:2048
	v_add_u32_e32 v0, s83, v0
	global_load_dwordx4 v[72:75], v0, s[96:97]
	global_load_dwordx4 v[76:79], v0, s[96:97] offset:2048
	v_add_u32_e32 v0, s83, v0
	global_load_dwordx4 v[80:83], v0, s[96:97]
	global_load_dwordx4 v[84:87], v0, s[96:97] offset:2048
	s_addk_i32 s86, 0xff80
	s_addk_i32 s87, 0x80
	s_add_i32 s81, s81, 1
	s_cmpk_lg_i32 s86, 0xfeff
	s_mov_b32 s75, s33
	s_waitcnt vmcnt(14)
	v_mov_b32_e32 v40, v211
	v_mov_b32_e32 v41, v212
	s_waitcnt lgkmcnt(0)
	s_barrier
	s_cbranch_scc0 .LBB0_651
	s_branch .LBB0_684
